# v32 + sc1 (write-through) on the norm loop's bf16 output stores so they are not left dirty for the L2 writeback at the next grid barrier
# speedup vs baseline: 1.0067x; 1.0026x over previous
.LBB0_74:
	global_load_dwordx4 v[12:15], v[4:5], off offset:-2048
	global_load_dwordx4 v[16:19], v[4:5], off offset:-1024
	global_load_dwordx4 v[20:23], v[4:5], off
	global_load_dwordx4 v[24:27], v[4:5], off offset:1024
	s_cmpk_lt_u32 s6, 0x2800
	s_cselect_b32 s0, s76, 0x3000
	s_cmpk_gt_i32 s6, 0x1fff
	s_cselect_b32 s0, s0, 0
	s_lshl_b32 s0, s0, 2
	s_add_u32 s0, s4, s0
	s_addc_u32 s1, s5, 0
	v_lshl_add_u64 v[84:85], s[0:1], 0, v[0:1]
	global_load_dwordx4 v[52:55], v0, s[0:1]
	v_lshl_add_u64 v[84:85], v[84:85], 0, s[12:13]
	s_add_i32 s6, s6, s70
	global_load_dwordx4 v[56:59], v[84:85], off
	global_load_dwordx4 v[60:63], v0, s[0:1] offset:1024
	global_load_dwordx4 v[64:67], v[84:85], off offset:1024
	global_load_dwordx4 v[68:71], v0, s[0:1] offset:2048
	global_load_dwordx4 v[72:75], v[84:85], off offset:2048
	global_load_dwordx4 v[76:79], v0, s[0:1] offset:3072
	global_load_dwordx4 v[80:83], v[84:85], off offset:3072
	s_cmpk_gt_i32 s6, 0x2fff
	s_waitcnt vmcnt(11)
	v_pk_mul_f32 v[40:41], v[14:15], v[14:15]
	v_pk_mul_f32 v[42:43], v[12:13], v[12:13]
	s_nop 0
	v_pk_mov_b32 v[44:45], v[42:43], v[40:41] op_sel:[1,0]
	v_mov_b32_e32 v43, v41
	v_pk_add_f32 v[28:29], v[44:45], v[42:43]
	s_nop 0
	v_pk_add_f32 v[28:29], v[28:29], v[28:29] op_sel:[0,1] op_sel_hi:[1,0]
	s_waitcnt vmcnt(10)
	v_pk_mul_f32 v[46:47], v[18:19], v[18:19]
	v_pk_mul_f32 v[48:49], v[16:17], v[16:17]
	s_nop 0
	v_pk_mov_b32 v[50:51], v[48:49], v[46:47] op_sel:[1,0]
	v_mov_b32_e32 v49, v47
	v_pk_add_f32 v[30:31], v[50:51], v[48:49]
	s_nop 0
	v_pk_add_f32 v[30:31], v[30:31], v[30:31] op_sel:[0,1] op_sel_hi:[1,0]
	v_lshl_add_u64 v[4:5], v[4:5], 0, s[96:97]
	s_waitcnt vmcnt(8)
	v_mul_f32_e32 v32, v24, v24
	v_mul_f32_e32 v33, v25, v25
	v_mov_b32_e32 v29, v32
	v_mov_b32_e32 v31, v33
	v_pk_add_f32 v[28:29], v[28:29], v[30:31]
	v_mul_f32_e32 v30, v21, v21
	v_mul_f32_e32 v32, v23, v23
	v_mul_f32_e32 v34, v26, v26
	v_mul_f32_e32 v35, v27, v27
	v_pk_fma_f32 v[30:31], v[20:21], v[20:21], v[30:31] op_sel_hi:[1,1,0]
	v_pk_fma_f32 v[32:33], v[22:23], v[22:23], v[32:33] op_sel_hi:[1,1,0]
	v_mov_b32_e32 v31, v34
	v_mov_b32_e32 v33, v35
	v_pk_add_f32 v[30:31], v[30:31], v[32:33]
	s_nop 0
	v_pk_add_f32 v[28:29], v[28:29], v[30:31]
	s_nop 0
	v_add_f32_e32 v28, v28, v29
	ds_bpermute_b32 v29, v6, v28
	s_waitcnt lgkmcnt(0)
	v_add_f32_e32 v28, v28, v29
	ds_bpermute_b32 v29, v7, v28
	s_waitcnt lgkmcnt(0)
	v_add_f32_e32 v28, v28, v29
	ds_bpermute_b32 v29, v8, v28
	s_waitcnt lgkmcnt(0)
	v_add_f32_e32 v28, v28, v29
	ds_bpermute_b32 v29, v9, v28
	s_waitcnt lgkmcnt(0)
	v_add_f32_e32 v28, v28, v29
	ds_bpermute_b32 v29, v10, v28
	s_waitcnt lgkmcnt(0)
	v_add_f32_e32 v28, v28, v29
	ds_bpermute_b32 v29, v11, v28
	s_waitcnt lgkmcnt(0)
	v_add_f32_e32 v28, v28, v29
	v_fmamk_f32 v28, v28, 0x3a800000, v213
	v_cmp_gt_f32_e32 vcc, s7, v28
	v_mul_f32_e32 v29, 0x4b800000, v28
	s_nop 0
	v_cndmask_b32_e32 v28, v28, v29, vcc
	v_rsq_f32_e32 v28, v28
	s_nop 0
	v_mul_f32_e32 v29, 0x45800000, v28
	v_cndmask_b32_e32 v36, v28, v29, vcc
	v_pk_mul_f32 v[12:13], v[12:13], v[36:37] op_sel_hi:[1,0]
	v_pk_mul_f32 v[14:15], v[14:15], v[36:37] op_sel_hi:[1,0]
	v_pk_mul_f32 v[16:17], v[16:17], v[36:37] op_sel_hi:[1,0]
	v_pk_mul_f32 v[18:19], v[18:19], v[36:37] op_sel_hi:[1,0]
	v_pk_mul_f32 v[20:21], v[20:21], v[36:37] op_sel_hi:[1,0]
	v_pk_mul_f32 v[22:23], v[22:23], v[36:37] op_sel_hi:[1,0]
	v_pk_mul_f32 v[24:25], v[24:25], v[36:37] op_sel_hi:[1,0]
	v_pk_mul_f32 v[26:27], v[26:27], v[36:37] op_sel_hi:[1,0]
	s_waitcnt vmcnt(6)
	v_pk_add_f32 v[58:59], v[58:59], 1.0 op_sel_hi:[1,0]
	v_pk_add_f32 v[56:57], v[56:57], 1.0 op_sel_hi:[1,0]
	v_pk_fma_f32 v[34:35], v[58:59], v[14:15], v[54:55]
	v_pk_fma_f32 v[32:33], v[56:57], v[12:13], v[52:53]
	s_waitcnt vmcnt(4)
	v_pk_add_f32 v[66:67], v[66:67], 1.0 op_sel_hi:[1,0]
	v_pk_add_f32 v[64:65], v[64:65], 1.0 op_sel_hi:[1,0]
	v_pk_fma_f32 v[30:31], v[66:67], v[18:19], v[62:63]
	v_pk_fma_f32 v[28:29], v[64:65], v[16:17], v[60:61]
	s_waitcnt vmcnt(2)
	v_pk_add_f32 v[74:75], v[74:75], 1.0 op_sel_hi:[1,0]
	v_pk_add_f32 v[72:73], v[72:73], 1.0 op_sel_hi:[1,0]
	v_pk_fma_f32 v[22:23], v[74:75], v[22:23], v[70:71]
	v_pk_fma_f32 v[20:21], v[72:73], v[20:21], v[68:69]
	s_waitcnt vmcnt(0)
	v_pk_add_f32 v[80:81], v[80:81], 1.0 op_sel_hi:[1,0]
	v_pk_add_f32 v[82:83], v[82:83], 1.0 op_sel_hi:[1,0]
	v_pk_fma_f32 v[12:13], v[80:81], v[24:25], v[76:77]
	v_cvt_pk_bf16_f32 v16, v32, v33
	v_cvt_pk_bf16_f32 v17, v34, v35
	v_pk_fma_f32 v[14:15], v[82:83], v[26:27], v[78:79]
	global_store_dwordx2 v[2:3], v[16:17], off offset:-1536 sc1
	v_cvt_pk_bf16_f32 v18, v28, v29
	v_cvt_pk_bf16_f32 v19, v30, v31
	global_store_dwordx2 v[2:3], v[18:19], off offset:-1024 sc1
	v_cvt_pk_bf16_f32 v40, v20, v21
	v_cvt_pk_bf16_f32 v41, v22, v23
	v_cvt_pk_bf16_f32 v12, v12, v13
	v_cvt_pk_bf16_f32 v13, v14, v15
	global_store_dwordx2 v[2:3], v[40:41], off offset:-512 sc1
	global_store_dwordx2 v[2:3], v[12:13], off sc1
	v_lshl_add_u64 v[2:3], v[2:3], 0, s[8:9]
	s_cbranch_scc0 .LBB0_74
